# replace 9 of 10 cooperative-groups grid syncs by XCD-hierarchical barrier on zeroed BUFA pad words (assumes 8 XCC x 32 WG)
# speedup vs baseline: 1.1338x; 1.1020x over previous
.LBB0_349:
	s_waitcnt vmcnt(0)
	s_waitcnt vmcnt(0)
	s_barrier
	s_and_saveexec_b64 s[6:7], s[0:1]
	s_cbranch_execz .LBB0_359
	s_sub_u32 s8, s94, 8
	s_subb_u32 s9, s95, 0
	s_load_dwordx2 s[8:9], s[8:9], 0x0
	s_getreg_b32 s10, hwreg(HW_REG_XCC_ID, 0, 4)
	v_mov_b32_e32 v3, 1
	s_lshl_b32 s10, s10, 12
	v_mov_b32_e32 v0, s10
	s_waitcnt lgkmcnt(0)
	s_add_u32 s8, s8, 0x8900c00
	s_addc_u32 s9, s9, 0
	v_mov_b32_e32 v2, 0x20000
	global_atomic_add v1, v0, v3, s[8:9] sc0
	s_waitcnt vmcnt(0)
	v_readfirstlane_b32 s11, v1
	v_add_u32_e32 v0, 0x10000, v0
	s_and_b32 s23, s11, 31
	s_lshr_b32 s22, s11, 5
	s_cmp_eq_u32 s23, 31
	s_cbranch_scc1 .Lgs2_lead
	s_mov_b32 s38, 0
.Lgs2_spin_a:
	s_sleep 1
	global_load_dword v1, v0, s[8:9] sc1
	s_add_u32 s38, s38, 1
	s_waitcnt vmcnt(0)
	v_readfirstlane_b32 s23, v1
	s_cmp_lg_u32 s23, s22
	s_cbranch_scc1 .Lgs2_acq
	s_cmp_lt_u32 s38, 0x20000
	s_cbranch_scc1 .Lgs2_spin_a
	s_branch .Lgs2_acq
.Lgs2_lead:
	buffer_wbl2 sc1
	s_waitcnt vmcnt(0)
	global_atomic_add v1, v2, v3, s[8:9] sc0
	s_waitcnt vmcnt(0)
	v_readfirstlane_b32 s11, v1
	v_mov_b32_e32 v2, 0x21000
	s_and_b32 s23, s11, 7
	s_lshr_b32 s22, s11, 3
	s_cmp_eq_u32 s23, 7
	s_cbranch_scc0 .Lgs2_spin_b0
	global_atomic_add v2, v3, s[8:9]
	s_branch .Lgs2_rel
.Lgs2_spin_b0:
	s_mov_b32 s38, 0
.Lgs2_spin_b:
	s_sleep 1
	global_load_dword v1, v2, s[8:9] sc1
	s_add_u32 s38, s38, 1
	s_waitcnt vmcnt(0)
	v_readfirstlane_b32 s23, v1
	s_cmp_lg_u32 s23, s22
	s_cbranch_scc1 .Lgs2_rel
	s_cmp_lt_u32 s38, 0x20000
	s_cbranch_scc1 .Lgs2_spin_b
.Lgs2_rel:
	global_atomic_add v0, v3, s[8:9]
.Lgs2_acq:
	buffer_inv sc1
	s_waitcnt vmcnt(0)

.LBB0_366:
	s_or_b64 exec, exec, s[10:11]
	s_barrier
	s_waitcnt vmcnt(0)
	s_barrier
	s_and_saveexec_b64 s[8:9], s[0:1]
	s_cbranch_execz .LBB0_376
	s_sub_u32 s10, s94, 8
	s_subb_u32 s11, s95, 0
	s_load_dwordx2 s[10:11], s[10:11], 0x0
	s_getreg_b32 s6, hwreg(HW_REG_XCC_ID, 0, 4)
	v_mov_b32_e32 v3, 1
	s_lshl_b32 s6, s6, 12
	v_mov_b32_e32 v0, s6
	s_waitcnt lgkmcnt(0)
	s_add_u32 s10, s10, 0x8900c00
	s_addc_u32 s11, s11, 0
	v_mov_b32_e32 v2, 0x20000
	global_atomic_add v1, v0, v3, s[10:11] sc0
	s_waitcnt vmcnt(0)
	v_readfirstlane_b32 s7, v1
	v_add_u32_e32 v0, 0x10000, v0
	s_and_b32 s23, s7, 31
	s_lshr_b32 s22, s7, 5
	s_cmp_eq_u32 s23, 31
	s_cbranch_scc1 .Lgs3_lead
	s_mov_b32 s38, 0
.Lgs3_spin_a:
	s_sleep 1
	global_load_dword v1, v0, s[10:11] sc1
	s_add_u32 s38, s38, 1
	s_waitcnt vmcnt(0)
	v_readfirstlane_b32 s23, v1
	s_cmp_lg_u32 s23, s22
	s_cbranch_scc1 .Lgs3_acq
	s_cmp_lt_u32 s38, 0x20000
	s_cbranch_scc1 .Lgs3_spin_a
	s_branch .Lgs3_acq
.Lgs3_lead:
	buffer_wbl2 sc1
	s_waitcnt vmcnt(0)
	global_atomic_add v1, v2, v3, s[10:11] sc0
	s_waitcnt vmcnt(0)
	v_readfirstlane_b32 s7, v1
	v_mov_b32_e32 v2, 0x21000
	s_and_b32 s23, s7, 7
	s_lshr_b32 s22, s7, 3
	s_cmp_eq_u32 s23, 7
	s_cbranch_scc0 .Lgs3_spin_b0
	global_atomic_add v2, v3, s[10:11]
	s_branch .Lgs3_rel

.Lgs3_spin_b:
	s_sleep 1
	global_load_dword v1, v2, s[10:11] sc1
	s_add_u32 s38, s38, 1
	s_waitcnt vmcnt(0)
	v_readfirstlane_b32 s23, v1
	s_cmp_lg_u32 s23, s22
	s_cbranch_scc1 .Lgs3_rel
	s_cmp_lt_u32 s38, 0x20000
	s_cbranch_scc1 .Lgs3_spin_b
.Lgs3_rel:
	global_atomic_add v0, v3, s[10:11]

.LBB0_394:
	s_or_b64 exec, exec, s[8:9]
	s_barrier
	s_waitcnt vmcnt(0)
	s_barrier
	s_and_saveexec_b64 s[6:7], s[0:1]
	s_cbranch_execz .LBB0_404
	s_sub_u32 s8, s94, 8
	s_subb_u32 s9, s95, 0
	s_load_dwordx2 s[8:9], s[8:9], 0x0
	s_getreg_b32 s10, hwreg(HW_REG_XCC_ID, 0, 4)
	v_mov_b32_e32 v3, 1
	s_lshl_b32 s10, s10, 12
	v_mov_b32_e32 v0, s10
	s_waitcnt lgkmcnt(0)
	s_add_u32 s8, s8, 0x8900c00
	s_addc_u32 s9, s9, 0
	v_mov_b32_e32 v2, 0x20000
	global_atomic_add v1, v0, v3, s[8:9] sc0
	s_waitcnt vmcnt(0)
	v_readfirstlane_b32 s11, v1
	v_add_u32_e32 v0, 0x10000, v0
	s_and_b32 s23, s11, 31
	s_lshr_b32 s22, s11, 5
	s_cmp_eq_u32 s23, 31
	s_cbranch_scc1 .Lgs4_lead
	s_mov_b32 s28, 0
.Lgs4_spin_a:
	s_sleep 1
	global_load_dword v1, v0, s[8:9] sc1
	s_add_u32 s28, s28, 1
	s_waitcnt vmcnt(0)
	v_readfirstlane_b32 s23, v1
	s_cmp_lg_u32 s23, s22
	s_cbranch_scc1 .Lgs4_acq
	s_cmp_lt_u32 s28, 0x20000
	s_cbranch_scc1 .Lgs4_spin_a
	s_branch .Lgs4_acq

.Lgs4_spin_b0:
	s_mov_b32 s28, 0
.Lgs4_spin_b:
	s_sleep 1
	global_load_dword v1, v2, s[8:9] sc1
	s_add_u32 s28, s28, 1
	s_waitcnt vmcnt(0)
	v_readfirstlane_b32 s23, v1
	s_cmp_lg_u32 s23, s22
	s_cbranch_scc1 .Lgs4_rel
	s_cmp_lt_u32 s28, 0x20000
	s_cbranch_scc1 .Lgs4_spin_b

.LBB0_461:
	s_barrier
	s_waitcnt vmcnt(0)
	s_barrier
	s_and_saveexec_b64 s[6:7], s[0:1]
	s_cbranch_execz .LBB0_471
	s_sub_u32 s8, s94, 8
	s_subb_u32 s9, s95, 0
	s_load_dwordx2 s[8:9], s[8:9], 0x0
	s_getreg_b32 s3, hwreg(HW_REG_XCC_ID, 0, 4)
	v_mov_b32_e32 v3, 1
	s_lshl_b32 s3, s3, 12
	v_mov_b32_e32 v0, s3
	s_waitcnt lgkmcnt(0)
	s_add_u32 s8, s8, 0x8900c00
	s_addc_u32 s9, s9, 0
	v_mov_b32_e32 v2, 0x20000
	global_atomic_add v1, v0, v3, s[8:9] sc0
	s_waitcnt vmcnt(0)
	v_readfirstlane_b32 s10, v1
	v_add_u32_e32 v0, 0x10000, v0
	s_and_b32 s22, s10, 31
	s_lshr_b32 s11, s10, 5
	s_cmp_eq_u32 s22, 31
	s_cbranch_scc1 .Lgs5_lead
	s_mov_b32 s23, 0
.Lgs5_spin_a:
	s_sleep 1
	global_load_dword v1, v0, s[8:9] sc1
	s_add_u32 s23, s23, 1
	s_waitcnt vmcnt(0)
	v_readfirstlane_b32 s22, v1
	s_cmp_lg_u32 s22, s11
	s_cbranch_scc1 .Lgs5_acq
	s_cmp_lt_u32 s23, 0x20000
	s_cbranch_scc1 .Lgs5_spin_a
	s_branch .Lgs5_acq
.Lgs5_lead:
	buffer_wbl2 sc1
	s_waitcnt vmcnt(0)
	global_atomic_add v1, v2, v3, s[8:9] sc0
	s_waitcnt vmcnt(0)
	v_readfirstlane_b32 s10, v1
	v_mov_b32_e32 v2, 0x21000
	s_and_b32 s22, s10, 7
	s_lshr_b32 s11, s10, 3
	s_cmp_eq_u32 s22, 7
	s_cbranch_scc0 .Lgs5_spin_b0
	global_atomic_add v2, v3, s[8:9]
	s_branch .Lgs5_rel
.Lgs5_spin_b0:
	s_mov_b32 s23, 0
.Lgs5_spin_b:
	s_sleep 1
	global_load_dword v1, v2, s[8:9] sc1
	s_add_u32 s23, s23, 1
	s_waitcnt vmcnt(0)
	v_readfirstlane_b32 s22, v1
	s_cmp_lg_u32 s22, s11
	s_cbranch_scc1 .Lgs5_rel
	s_cmp_lt_u32 s23, 0x20000
	s_cbranch_scc1 .Lgs5_spin_b

.LBB0_497:
	s_waitcnt vmcnt(0)
	s_waitcnt vmcnt(0)
	s_barrier
	s_and_saveexec_b64 s[6:7], s[0:1]
	s_cbranch_execz .LBB0_507
	s_sub_u32 s8, s94, 8
	s_subb_u32 s9, s95, 0
	s_load_dwordx2 s[8:9], s[8:9], 0x0
	s_getreg_b32 s3, hwreg(HW_REG_XCC_ID, 0, 4)
	v_mov_b32_e32 v3, 1
	s_lshl_b32 s3, s3, 12
	v_mov_b32_e32 v0, s3
	s_waitcnt lgkmcnt(0)
	s_add_u32 s8, s8, 0x8900c00
	s_addc_u32 s9, s9, 0
	v_mov_b32_e32 v2, 0x20000
	global_atomic_add v1, v0, v3, s[8:9] sc0
	s_waitcnt vmcnt(0)
	v_readfirstlane_b32 s10, v1
	v_add_u32_e32 v0, 0x10000, v0
	s_and_b32 s12, s10, 31
	s_lshr_b32 s11, s10, 5
	s_cmp_eq_u32 s12, 31
	s_cbranch_scc1 .Lgs6_lead
	s_mov_b32 s13, 0
.Lgs6_spin_a:
	s_sleep 1
	global_load_dword v1, v0, s[8:9] sc1
	s_add_u32 s13, s13, 1
	s_waitcnt vmcnt(0)
	v_readfirstlane_b32 s12, v1
	s_cmp_lg_u32 s12, s11
	s_cbranch_scc1 .Lgs6_acq
	s_cmp_lt_u32 s13, 0x20000
	s_cbranch_scc1 .Lgs6_spin_a
	s_branch .Lgs6_acq
.Lgs6_lead:
	buffer_wbl2 sc1
	s_waitcnt vmcnt(0)
	global_atomic_add v1, v2, v3, s[8:9] sc0
	s_waitcnt vmcnt(0)
	v_readfirstlane_b32 s10, v1
	v_mov_b32_e32 v2, 0x21000
	s_and_b32 s12, s10, 7
	s_lshr_b32 s11, s10, 3
	s_cmp_eq_u32 s12, 7
	s_cbranch_scc0 .Lgs6_spin_b0
	global_atomic_add v2, v3, s[8:9]
	s_branch .Lgs6_rel
.Lgs6_spin_b0:
	s_mov_b32 s13, 0
.Lgs6_spin_b:
	s_sleep 1
	global_load_dword v1, v2, s[8:9] sc1
	s_add_u32 s13, s13, 1
	s_waitcnt vmcnt(0)
	v_readfirstlane_b32 s12, v1
	s_cmp_lg_u32 s12, s11
	s_cbranch_scc1 .Lgs6_rel
	s_cmp_lt_u32 s13, 0x20000
	s_cbranch_scc1 .Lgs6_spin_b

.LBB0_512:
	s_or_b64 exec, exec, s[8:9]
	s_waitcnt vmcnt(0)
	s_barrier
	s_and_saveexec_b64 s[8:9], s[0:1]
	s_cbranch_execz .LBB0_522
	s_sub_u32 s10, s94, 8
	s_subb_u32 s11, s95, 0
	s_load_dwordx2 s[10:11], s[10:11], 0x0
	s_getreg_b32 s3, hwreg(HW_REG_XCC_ID, 0, 4)
	v_mov_b32_e32 v3, 1
	s_lshl_b32 s3, s3, 12
	v_mov_b32_e32 v0, s3
	s_waitcnt lgkmcnt(0)
	s_add_u32 s10, s10, 0x8900c00
	s_addc_u32 s11, s11, 0
	v_mov_b32_e32 v2, 0x20000
	global_atomic_add v1, v0, v3, s[10:11] sc0
	s_waitcnt vmcnt(0)
	v_readfirstlane_b32 s12, v1
	v_add_u32_e32 v0, 0x10000, v0
	s_and_b32 s14, s12, 31
	s_lshr_b32 s13, s12, 5
	s_cmp_eq_u32 s14, 31
	s_cbranch_scc1 .Lgs7_lead
	s_mov_b32 s15, 0
.Lgs7_spin_a:
	s_sleep 1
	global_load_dword v1, v0, s[10:11] sc1
	s_add_u32 s15, s15, 1
	s_waitcnt vmcnt(0)
	v_readfirstlane_b32 s14, v1
	s_cmp_lg_u32 s14, s13
	s_cbranch_scc1 .Lgs7_acq
	s_cmp_lt_u32 s15, 0x20000
	s_cbranch_scc1 .Lgs7_spin_a
	s_branch .Lgs7_acq
.Lgs7_lead:
	buffer_wbl2 sc1
	s_waitcnt vmcnt(0)
	global_atomic_add v1, v2, v3, s[10:11] sc0
	s_waitcnt vmcnt(0)
	v_readfirstlane_b32 s12, v1
	v_mov_b32_e32 v2, 0x21000
	s_and_b32 s14, s12, 7
	s_lshr_b32 s13, s12, 3
	s_cmp_eq_u32 s14, 7
	s_cbranch_scc0 .Lgs7_spin_b0
	global_atomic_add v2, v3, s[10:11]
	s_branch .Lgs7_rel
.Lgs7_spin_b0:
	s_mov_b32 s15, 0
.Lgs7_spin_b:
	s_sleep 1
	global_load_dword v1, v2, s[10:11] sc1
	s_add_u32 s15, s15, 1
	s_waitcnt vmcnt(0)
	v_readfirstlane_b32 s14, v1
	s_cmp_lg_u32 s14, s13
	s_cbranch_scc1 .Lgs7_rel
	s_cmp_lt_u32 s15, 0x20000
	s_cbranch_scc1 .Lgs7_spin_b

.LBB0_846:
	s_waitcnt vmcnt(0)
	s_waitcnt vmcnt(0)
	s_barrier
	s_and_saveexec_b64 s[8:9], s[0:1]
	s_cbranch_execz .LBB0_856
	s_sub_u32 s10, s94, 8
	s_subb_u32 s11, s95, 0
	s_load_dwordx2 s[10:11], s[10:11], 0x0
	s_getreg_b32 s12, hwreg(HW_REG_XCC_ID, 0, 4)
	v_mov_b32_e32 v3, 1
	s_lshl_b32 s12, s12, 12
	v_mov_b32_e32 v0, s12
	s_waitcnt lgkmcnt(0)
	s_add_u32 s10, s10, 0x8900c00
	s_addc_u32 s11, s11, 0
	v_mov_b32_e32 v2, 0x20000
	global_atomic_add v1, v0, v3, s[10:11] sc0
	s_waitcnt vmcnt(0)
	v_readfirstlane_b32 s13, v1
	v_add_u32_e32 v0, 0x10000, v0
	s_and_b32 s15, s13, 31
	s_lshr_b32 s14, s13, 5
	s_cmp_eq_u32 s15, 31
	s_cbranch_scc1 .Lgs8_lead
	s_mov_b32 s16, 0
.Lgs8_spin_a:
	s_sleep 1
	global_load_dword v1, v0, s[10:11] sc1
	s_add_u32 s16, s16, 1
	s_waitcnt vmcnt(0)
	v_readfirstlane_b32 s15, v1
	s_cmp_lg_u32 s15, s14
	s_cbranch_scc1 .Lgs8_acq
	s_cmp_lt_u32 s16, 0x20000
	s_cbranch_scc1 .Lgs8_spin_a
	s_branch .Lgs8_acq
.Lgs8_lead:
	buffer_wbl2 sc1
	s_waitcnt vmcnt(0)
	global_atomic_add v1, v2, v3, s[10:11] sc0
	s_waitcnt vmcnt(0)
	v_readfirstlane_b32 s13, v1
	v_mov_b32_e32 v2, 0x21000
	s_and_b32 s15, s13, 7
	s_lshr_b32 s14, s13, 3
	s_cmp_eq_u32 s15, 7
	s_cbranch_scc0 .Lgs8_spin_b0
	global_atomic_add v2, v3, s[10:11]
	s_branch .Lgs8_rel
.Lgs8_spin_b0:
	s_mov_b32 s16, 0
.Lgs8_spin_b:
	s_sleep 1
	global_load_dword v1, v2, s[10:11] sc1
	s_add_u32 s16, s16, 1
	s_waitcnt vmcnt(0)
	v_readfirstlane_b32 s15, v1
	s_cmp_lg_u32 s15, s14
	s_cbranch_scc1 .Lgs8_rel
	s_cmp_lt_u32 s16, 0x20000
	s_cbranch_scc1 .Lgs8_spin_b

.LBB0_895:
	s_barrier
	s_waitcnt vmcnt(0)
	s_barrier
	s_and_saveexec_b64 s[8:9], s[0:1]
	s_cbranch_execz .LBB0_905
	s_sub_u32 s10, s94, 8
	s_subb_u32 s11, s95, 0
	s_load_dwordx2 s[10:11], s[10:11], 0x0
	s_getreg_b32 s3, hwreg(HW_REG_XCC_ID, 0, 4)
	v_mov_b32_e32 v3, 1
	s_lshl_b32 s3, s3, 12
	v_mov_b32_e32 v0, s3
	s_waitcnt lgkmcnt(0)
	s_add_u32 s10, s10, 0x8900c00
	s_addc_u32 s11, s11, 0
	v_mov_b32_e32 v2, 0x20000
	global_atomic_add v1, v0, v3, s[10:11] sc0
	s_waitcnt vmcnt(0)
	v_readfirstlane_b32 s12, v1
	v_add_u32_e32 v0, 0x10000, v0
	s_and_b32 s14, s12, 31
	s_lshr_b32 s13, s12, 5
	s_cmp_eq_u32 s14, 31
	s_cbranch_scc1 .Lgs9_lead
	s_mov_b32 s15, 0

.LBB0_931:
	s_waitcnt vmcnt(0)
	s_waitcnt vmcnt(0)
	s_barrier
	s_and_saveexec_b64 s[2:3], s[0:1]
	s_cbranch_execz .LBB0_941
	s_sub_u32 s0, s94, 8
	s_subb_u32 s1, s95, 0
	s_load_dwordx2 s[0:1], s[0:1], 0x0
	s_getreg_b32 s8, hwreg(HW_REG_XCC_ID, 0, 4)
	v_mov_b32_e32 v3, 1
	s_lshl_b32 s8, s8, 12
	v_mov_b32_e32 v0, s8
	s_waitcnt lgkmcnt(0)
	s_add_u32 s0, s0, 0x8900c00
	s_addc_u32 s1, s1, 0
	v_mov_b32_e32 v2, 0x20000
	global_atomic_add v1, v0, v3, s[0:1] sc0
	s_waitcnt vmcnt(0)
	v_readfirstlane_b32 s9, v1
	v_add_u32_e32 v0, 0x10000, v0
	s_and_b32 s11, s9, 31
	s_lshr_b32 s10, s9, 5
	s_cmp_eq_u32 s11, 31
	s_cbranch_scc1 .Lgs10_lead
	s_mov_b32 s12, 0
.Lgs10_spin_a:
	s_sleep 1
	global_load_dword v1, v0, s[0:1] sc1
	s_add_u32 s12, s12, 1
	s_waitcnt vmcnt(0)
	v_readfirstlane_b32 s11, v1
	s_cmp_lg_u32 s11, s10
	s_cbranch_scc1 .Lgs10_acq
	s_cmp_lt_u32 s12, 0x20000
	s_cbranch_scc1 .Lgs10_spin_a
	s_branch .Lgs10_acq
.Lgs10_lead:
	buffer_wbl2 sc1
	s_waitcnt vmcnt(0)
	global_atomic_add v1, v2, v3, s[0:1] sc0
	s_waitcnt vmcnt(0)
	v_readfirstlane_b32 s9, v1
	v_mov_b32_e32 v2, 0x21000
	s_and_b32 s11, s9, 7
	s_lshr_b32 s10, s9, 3
	s_cmp_eq_u32 s11, 7
	s_cbranch_scc0 .Lgs10_spin_b0
	global_atomic_add v2, v3, s[0:1]
	s_branch .Lgs10_rel
.Lgs10_spin_b0:
	s_mov_b32 s12, 0
.Lgs10_spin_b:
	s_sleep 1
	global_load_dword v1, v2, s[0:1] sc1
	s_add_u32 s12, s12, 1
	s_waitcnt vmcnt(0)
	v_readfirstlane_b32 s11, v1
	s_cmp_lg_u32 s11, s10
	s_cbranch_scc1 .Lgs10_rel
	s_cmp_lt_u32 s12, 0x20000
	s_cbranch_scc1 .Lgs10_spin_b
.Lgs10_rel:
	global_atomic_add v0, v3, s[0:1]
